# conv31 parameter loads issued before the conv3 seam fix-up, and the seam fix-up itself runs while conv31's first window loads are in flight (its VGPRs renamed to free conv31 registers)
# speedup vs baseline: 1.0759x; 1.0031x over previous
; template <int PH> ...
;     ...
;     const f32x2 bias = *(const f32x2*)(cb + c2);
;     f32x2 outv[16];
; #pragma unroll
;     for (int t = 0; t < 16; ++t) outv[t] = bias;
; #pragma unroll
;     for (int ps = 0; ps < 2; ++ps) {
;         const int kb = ps * 16, ntap = ps == 0 ? 16 : 15;
;         f32x2 w[16];
; #pragma unroll
;         for (int k = 0; k < 16; ++k) if (k < ntap) w[k] = *(const f32x2*)(cw + (kb + k) * 1024 + c2);
; #pragma unroll
;         for (int r = 0; r < 31; ++r) if (r < ntap + 15) {
;             const unsigned v = *(const LAS unsigned*)(lds + ((34 + 16 * PH + kb + r) & 63) * 2048 + tid * 4);
;             const f32x2 x = (f32x2){bf_lo(v), bf_hi(v)};
; #pragma unroll
;             for (int t = 0; t < 16; ++t) { const int k = r - t; if (k >= 0 && k < ntap) outv[t] = __builtin_elementwise_fma(w[k], x, outv[t]); }
;             if ((r & 7) == 7) asm volatile("" ::: "memory");
;         }
;     }
;     {
;         float s[16], q[16];
; #pragma unroll
;         for (int t = 0; t < 16; ++t) { s[t] = outv[t][0] + outv[t][1]; q[t] = outv[t][0] * outv[t][0] + outv[t][1] * outv[t][1]; }
; #pragma unroll
;         for (int lvl = 0; lvl < 4; ++lvl) {
;             const int half = 8 >> lvl, off = 32 >> lvl; const bool hi = (lane & off) != 0;
; #pragma unroll
;             for (int i = 0; i < half; ++i) {
;                 const float ks = hi ? s[i + half] : s[i], ss = hi ? s[i] : s[i + half]; s[i] = ks + __shfl_xor(ss, off);
;                 const float kq = hi ? q[i + half] : q[i], sq = hi ? q[i] : q[i + half]; q[i] = kq + __shfl_xor(sq, off);
;             }
;         }
;         s[0] += __shfl_xor(s[0], 2); q[0] += __shfl_xor(q[0], 2);
;         s[0] += __shfl_xor(s[0], 1); q[0] += __shfl_xor(q[0], 1);
;         if ((lane & 3) == 0) *(LAS f32x2*)(red + ((lane >> 2) * 8 + wid) * 2) = (f32x2){s[0], q[0]};
;     }
;     __syncthreads();
;     if (has_next) {
; #pragma unroll
;         for (int q = 0; q < 4; ++q) { const int i = tid + q * 512; *(LAS u32x4*)(lds + ((34 + 16 * PH + 46 + (i >> 7)) & 63) * 2048 + (i & 127) * 16) = nx[q]; }
;     }
;     if (tid < 16) {
;         float S = 0.f, Q2 = 0.f;
; #pragma unroll
;         for (int wv = 0; wv < 8; ++wv) { const f32x2 t = *(const LAS f32x2*)(red + (tid * 8 + wv) * 2); S += t[0]; Q2 += t[1]; }
;         const float mean = S * (1.f / 1024.f), var = fmaxf(Q2 * (1.f / 1024.f) - mean * mean, 0.f);
.LBB0_347:
	s_or_b64 exec, exec, s[0:1]
	s_waitcnt lgkmcnt(0)
	s_barrier
	v_mbcnt_lo_u32_b32 v224, -1, 0
	v_mbcnt_hi_u32_b32 v224, -1, v224
	v_add_u32_e32 v225, s87, v224
	v_lshlrev_b32_e32 v226, 2, v225
	v_lshlrev_b32_e32 v227, 3, v225
	s_mov_b64 s[100:101], s[48:49]
	global_load_dwordx2 v[92:93], v227, s[100:101]
	s_add_u32 s100, s100, 0x1000
	s_addc_u32 s101, s101, 0
	global_load_dwordx2 v[94:95], v227, s[100:101]
	s_add_u32 s100, s100, 0x1000
	s_addc_u32 s101, s101, 0
	global_load_dwordx2 v[96:97], v227, s[100:101]
	s_add_u32 s100, s100, 0x1000
	s_addc_u32 s101, s101, 0
	global_load_dwordx2 v[98:99], v227, s[100:101]
	s_add_u32 s100, s100, 0x1000
	s_addc_u32 s101, s101, 0
	global_load_dwordx2 v[100:101], v227, s[100:101]
	s_add_u32 s100, s100, 0x1000
	s_addc_u32 s101, s101, 0
	global_load_dwordx2 v[102:103], v227, s[100:101]
	s_add_u32 s100, s100, 0x1000
	s_addc_u32 s101, s101, 0
	global_load_dwordx2 v[104:105], v227, s[100:101]
	s_add_u32 s100, s100, 0x1000
	s_addc_u32 s101, s101, 0
	global_load_dwordx2 v[106:107], v227, s[100:101]
	s_add_u32 s100, s100, 0x1000
	s_addc_u32 s101, s101, 0
	global_load_dwordx2 v[108:109], v227, s[100:101]
	s_add_u32 s100, s100, 0x1000
	s_addc_u32 s101, s101, 0
	global_load_dwordx2 v[110:111], v227, s[100:101]
	s_add_u32 s100, s100, 0x1000
	s_addc_u32 s101, s101, 0
	global_load_dwordx2 v[112:113], v227, s[100:101]
	s_add_u32 s100, s100, 0x1000
	s_addc_u32 s101, s101, 0
	global_load_dwordx2 v[114:115], v227, s[100:101]
	s_add_u32 s100, s100, 0x1000
	s_addc_u32 s101, s101, 0
	global_load_dwordx2 v[116:117], v227, s[100:101]
	s_add_u32 s100, s100, 0x1000
	s_addc_u32 s101, s101, 0
	global_load_dwordx2 v[118:119], v227, s[100:101]
	s_add_u32 s100, s100, 0x1000
	s_addc_u32 s101, s101, 0
	global_load_dwordx2 v[120:121], v227, s[100:101]
	s_add_u32 s100, s100, 0x1000
	s_addc_u32 s101, s101, 0
	global_load_dwordx2 v[122:123], v227, s[100:101]
	s_add_u32 s100, s100, 0x1000
	s_addc_u32 s101, s101, 0
	global_load_dwordx2 v[124:125], v227, s[100:101]
	s_add_u32 s100, s100, 0x1000
	s_addc_u32 s101, s101, 0
	global_load_dwordx2 v[126:127], v227, s[100:101]
	s_add_u32 s100, s100, 0x1000
	s_addc_u32 s101, s101, 0
	global_load_dwordx2 v[128:129], v227, s[100:101]
	s_add_u32 s100, s100, 0x1000
	s_addc_u32 s101, s101, 0
	global_load_dwordx2 v[130:131], v227, s[100:101]
	s_add_u32 s100, s100, 0x1000
	s_addc_u32 s101, s101, 0
	global_load_dwordx2 v[132:133], v227, s[100:101]
	s_add_u32 s100, s100, 0x1000
	s_addc_u32 s101, s101, 0
	global_load_dwordx2 v[134:135], v227, s[100:101]
	s_add_u32 s100, s100, 0x1000
	s_addc_u32 s101, s101, 0
	global_load_dwordx2 v[136:137], v227, s[100:101]
	s_add_u32 s100, s100, 0x1000
	s_addc_u32 s101, s101, 0
	global_load_dwordx2 v[138:139], v227, s[100:101]
	s_add_u32 s100, s100, 0x1000
	s_addc_u32 s101, s101, 0
	global_load_dwordx2 v[140:141], v227, s[100:101]
	s_add_u32 s100, s100, 0x1000
	s_addc_u32 s101, s101, 0
	global_load_dwordx2 v[142:143], v227, s[100:101]
	s_add_u32 s100, s100, 0x1000
	s_addc_u32 s101, s101, 0
	global_load_dwordx2 v[144:145], v227, s[100:101]
	s_add_u32 s100, s100, 0x1000
	s_addc_u32 s101, s101, 0
	global_load_dwordx2 v[146:147], v227, s[100:101]
	s_add_u32 s100, s100, 0x1000
	s_addc_u32 s101, s101, 0
	global_load_dwordx2 v[148:149], v227, s[100:101]
	s_add_u32 s100, s100, 0x1000
	s_addc_u32 s101, s101, 0
	global_load_dwordx2 v[150:151], v227, s[100:101]
	s_add_u32 s100, s100, 0x1000
	s_addc_u32 s101, s101, 0
	global_load_dwordx2 v[152:153], v227, s[100:101]
	global_load_dwordx2 v[218:219], v227, s[50:51]
	global_load_dwordx2 v[220:221], v227, s[8:9]
	global_load_dwordx2 v[222:223], v227, s[10:11]
	s_cmpk_gt_i32 s2, 0xff
	s_cbranch_scc1 .Lc31_done
; #define LAS __attribute__((address_space(3)))
; __device__ __forceinline__ void conv31_phase(LAS unsigned char* lds, const bf16_t* GLU, bf16_t* SZB, const float* cw, const float* cb, const float* lng, const float* lnb, int G, int c, const int widx) {
;     ...
;     for (int run = c; run < NTOK / 128; run += G) {
;         const int T0 = run * 128, tpos = T0 & (SEQ - 1);
;         __syncthreads();
; #pragma unroll
;         for (int h = 0; h < 2; ++h) {
;             int tf = tid; asm volatile("" : "+v"(tf));
;             u32x4 tv[6];
; #pragma unroll
;             for (int q = 0; q < 6; ++q) { const int i = tf + (h * 6 + q) * 512, r = (i >> 7) < 46 ? (i >> 7) : 45; const int gr = (tpos - 30 + r >= 0) ? (T0 - 30 + r) : T0;
;                 tv[q] = *(const u32x4*)(GLU + (size_t)gr * 1024 + (i & 127) * 8); }
; #pragma unroll
;             for (int q = 0; q < 6; ++q) { const int i = tf + (h * 6 + q) * 512, r = i >> 7;
;                 if (r < 46) *(LAS u32x4*)(lds + ((34 + r) & 63) * 2048 + (i & 127) * 16) = (tpos - 30 + r >= 0) ? tv[q] : (u32x4){0u, 0u, 0u, 0u}; }
	v_mov_b32_e32 v254, 0
	v_lshrrev_b32_e32 v253, 4, v224
	v_lshlrev_b32_e32 v253, 7, v253
	s_lshr_b32 s4, s87, 3
	v_add_u32_e32 v253, s4, v253
	s_lshl_b32 s6, s2, 7
	s_mov_b32 s54, 0xbfb8aa3b
	s_mov_b32 s55, 0xbfb8aa3b
	s_and_b32 s4, s6, 0x1fff
	s_cmp_eq_u32 s4, 0
	s_cbranch_scc1 .Lc31_seqstart
	s_sub_i32 s100, s6, 30
	s_ashr_i32 s101, s100, 31
	s_lshl_b64 s[100:101], s[100:101], 11
	s_add_u32 s100, s100, s14
	s_addc_u32 s101, s101, s15
	global_load_dword v0, v226, s[100:101]
	global_load_dword v2, v226, s[100:101] offset:2048
	s_add_u32 s100, s100, 0x1000
	s_addc_u32 s101, s101, 0
	global_load_dword v4, v226, s[100:101]
	global_load_dword v6, v226, s[100:101] offset:2048
	s_add_u32 s100, s100, 0x1000
	s_addc_u32 s101, s101, 0
	global_load_dword v8, v226, s[100:101]
	global_load_dword v10, v226, s[100:101] offset:2048
	s_add_u32 s100, s100, 0x1000
	s_addc_u32 s101, s101, 0
	global_load_dword v12, v226, s[100:101]
	global_load_dword v14, v226, s[100:101] offset:2048
	s_add_u32 s100, s100, 0x1000
	s_addc_u32 s101, s101, 0
	global_load_dword v16, v226, s[100:101]
	global_load_dword v18, v226, s[100:101] offset:2048
	s_add_u32 s100, s100, 0x1000
	s_addc_u32 s101, s101, 0
	global_load_dword v20, v226, s[100:101]
	global_load_dword v22, v226, s[100:101] offset:2048
	s_add_u32 s100, s100, 0x1000
	s_addc_u32 s101, s101, 0
	global_load_dword v24, v226, s[100:101]
	global_load_dword v26, v226, s[100:101] offset:2048
	s_add_u32 s100, s100, 0x1000
	s_addc_u32 s101, s101, 0
	global_load_dword v28, v226, s[100:101]
	global_load_dword v30, v226, s[100:101] offset:2048
	s_add_u32 s100, s100, 0x1000
	s_addc_u32 s101, s101, 0
	global_load_dword v32, v226, s[100:101]
	global_load_dword v34, v226, s[100:101] offset:2048
	s_add_u32 s100, s100, 0x1000
	s_addc_u32 s101, s101, 0
	global_load_dword v36, v226, s[100:101]
	global_load_dword v38, v226, s[100:101] offset:2048
	s_add_u32 s100, s100, 0x1000
	s_addc_u32 s101, s101, 0
	global_load_dword v40, v226, s[100:101]
	global_load_dword v42, v226, s[100:101] offset:2048
	s_add_u32 s100, s100, 0x1000
	s_addc_u32 s101, s101, 0
	global_load_dword v44, v226, s[100:101]
	global_load_dword v46, v226, s[100:101] offset:2048
	s_add_u32 s100, s100, 0x1000
	s_addc_u32 s101, s101, 0
	global_load_dword v48, v226, s[100:101]
	global_load_dword v50, v226, s[100:101] offset:2048
	s_add_u32 s100, s100, 0x1000
	s_addc_u32 s101, s101, 0
	global_load_dword v52, v226, s[100:101]
	global_load_dword v54, v226, s[100:101] offset:2048
	s_add_u32 s100, s100, 0x1000
	s_addc_u32 s101, s101, 0
	global_load_dword v56, v226, s[100:101]
	global_load_dword v58, v226, s[100:101] offset:2048
	s_add_u32 s100, s100, 0x1000
	s_addc_u32 s101, s101, 0
	global_load_dword v60, v226, s[100:101]
	global_load_dword v62, v226, s[100:101] offset:2048
	s_add_u32 s100, s100, 0x1000
	s_addc_u32 s101, s101, 0
	global_load_dword v64, v226, s[100:101]
	global_load_dword v66, v226, s[100:101] offset:2048
	s_add_u32 s100, s100, 0x1000
	s_addc_u32 s101, s101, 0
	global_load_dword v68, v226, s[100:101]
	global_load_dword v70, v226, s[100:101] offset:2048
	s_add_u32 s100, s100, 0x1000
	s_addc_u32 s101, s101, 0
	global_load_dword v72, v226, s[100:101]
	global_load_dword v74, v226, s[100:101] offset:2048
	s_add_u32 s100, s100, 0x1000
	s_addc_u32 s101, s101, 0
	global_load_dword v76, v226, s[100:101]
	global_load_dword v78, v226, s[100:101] offset:2048
	s_add_u32 s100, s100, 0x1000
	s_addc_u32 s101, s101, 0
	global_load_dword v80, v226, s[100:101]
	global_load_dword v82, v226, s[100:101] offset:2048
	s_add_u32 s100, s100, 0x1000
	s_addc_u32 s101, s101, 0
	global_load_dword v84, v226, s[100:101]
	global_load_dword v86, v226, s[100:101] offset:2048
	s_add_u32 s100, s100, 0x1000
	s_addc_u32 s101, s101, 0
	global_load_dword v88, v226, s[100:101]
	global_load_dword v90, v226, s[100:101] offset:2048
	s_branch .Lc31_filled

; __device__ __forceinline__ u32x2 pk4(f32x4 v) { u32x2 r; r.x = pk_bf16(v[0], v[1]); r.y = pk_bf16(v[2], v[3]); return r; }
; __device__ __forceinline__ f32x4 unpk4(u32x2 v) { return (f32x4){bf_lo(v.x), bf_hi(v.x), bf_lo(v.y), bf_hi(v.y)}; }
; __device__ __forceinline__ int tid_of(int widx) { int l; asm volatile("v_mbcnt_lo_u32_b32 %0, -1, 0\n\tv_mbcnt_hi_u32_b32 %0, -1, %0" : "=v"(l)); return widx * 64 + l; }
; __global__ void __launch_bounds__(512, 2) fwd_megakernel(Params p) {
;     ...
;         int tid_ = tid_of(widx); asm volatile("" : "+v"(tid_)); const int tid = tid_;
;         for (int i = bx * 512 + tid; i < 512 * 256; i += G * 512) {
;             const int blk = i >> 8, ch = (i & 255) * 4;
;             if ((blk & 127) != 0) {
;                 const f32x4 w0 = *(const f32x4*)(conv_a_w + ch), w1 = *(const f32x4*)(conv_a_w + 1024 + ch);
;                 const f32x4 pt0 = unpk4(*(const u32x2*)(PAT + (size_t)((blk - 1) * 2 + 0) * 1024 + ch)), pt1 = unpk4(*(const u32x2*)(PAT + (size_t)((blk - 1) * 2 + 1) * 1024 + ch));
;                 const f32x4 g0 = unpk4(*(const u32x2*)(GAH + (size_t)(blk * 2 + 0) * 1024 + ch)), g1 = unpk4(*(const u32x2*)(GAH + (size_t)(blk * 2 + 1) * 1024 + ch));
;                 u32x2* h0 = (u32x2*)(HA + (size_t)(blk * 64) * 1024 + ch); u32x2* h1 = (u32x2*)(HA + (size_t)(blk * 64 + 1) * 1024 + ch);
;                 *h0 = pk4(unpk4(*h0) + g0 * (w1 * pt1 + w0 * pt0));
;                 *h1 = pk4(unpk4(*h1) + g1 * (w0 * pt1));
;             }
;         }
.Lc31_filled:
	s_mov_b32 s98, s6
	v_mbcnt_lo_u32_b32 v154, -1, 0
	v_mbcnt_hi_u32_b32 v154, -1, v154
	s_mov_b32 s0, 0x20000
	v_add_u32_e32 v154, s87, v154
	s_nop 0
	v_add_u32_e32 v156, s68, v154
	v_cmp_gt_i32_e32 vcc, s0, v156
	s_and_saveexec_b64 s[0:1], vcc
	s_cbranch_execz .LBB0_352
	s_add_u32 s4, s44, 0x1000
	v_lshlrev_b32_e32 v154, 2, v154
	s_addc_u32 s5, s45, 0
	s_lshl_b32 s12, s3, 9
	v_lshl_add_u32 v157, s2, 11, v154
	s_lshl_b32 s13, s3, 11
	s_mov_b64 s[6:7], 0
	v_mov_b32_e32 v155, 0
	s_mov_b32 s30, 0x1ffff
	s_branch .LBB0_350
.LBB0_349:
	s_or_b64 exec, exec, s[28:29]
	v_add_u32_e32 v156, s12, v156
	v_cmp_lt_i32_e32 vcc, s30, v156
	s_or_b64 s[6:7], vcc, s[6:7]
	v_add_u32_e32 v157, s13, v157
	s_andn2_b64 exec, exec, s[6:7]
	s_cbranch_execz .LBB0_352
.LBB0_350:
	v_and_b32_e32 v154, 0x7f00, v156
	v_cmp_ne_u32_e32 vcc, 0, v154
	s_and_saveexec_b64 s[28:29], vcc
	s_cbranch_execz .LBB0_349
	v_ashrrev_i32_e32 v172, 8, v156
	v_lshlrev_b32_e32 v162, 1, v172
	v_ashrrev_i32_e32 v163, 31, v162
	v_and_b32_e32 v154, 0x3fc, v157
	v_lshlrev_b64 v[164:165], 11, v[162:163]
	v_lshlrev_b32_e32 v182, 2, v154
	v_lshlrev_b32_e32 v154, 1, v154
	v_lshl_add_u64 v[166:167], s[58:59], 0, v[164:165]
	v_lshl_add_u64 v[164:165], s[60:61], 0, v[164:165]
	v_lshl_add_u64 v[166:167], v[166:167], 0, v[154:155]
	v_lshl_add_u64 v[164:165], v[164:165], 0, v[154:155]
	global_load_dwordx4 v[158:161], v182, s[4:5]
	global_load_dwordx2 v[168:169], v[166:167], off offset:-4096
	s_nop 0
	global_load_dwordx2 v[166:167], v[166:167], off offset:-2048
	s_nop 0
	global_load_dwordx2 v[170:171], v[164:165], off
	v_or_b32_e32 v162, 1, v162
	v_lshlrev_b32_e32 v164, 6, v172
	v_ashrrev_i32_e32 v163, 31, v162
	v_ashrrev_i32_e32 v165, 31, v164
	v_lshlrev_b64 v[172:173], 11, v[164:165]
	v_lshlrev_b64 v[162:163], 11, v[162:163]
	v_lshl_add_u64 v[172:173], s[90:91], 0, v[172:173]
	v_lshl_add_u64 v[162:163], s[60:61], 0, v[162:163]
	v_lshl_add_u64 v[172:173], v[172:173], 0, v[154:155]
	v_lshl_add_u64 v[162:163], v[162:163], 0, v[154:155]
	global_load_dwordx2 v[174:175], v[172:173], off
	global_load_dwordx2 v[176:177], v[162:163], off
	v_or_b32_e32 v162, 1, v164
	v_ashrrev_i32_e32 v163, 31, v162
	v_lshlrev_b64 v[162:163], 11, v[162:163]
	v_lshl_add_u64 v[162:163], s[90:91], 0, v[162:163]
	v_lshl_add_u64 v[178:179], v[162:163], 0, v[154:155]
	global_load_dwordx2 v[180:181], v[178:179], off
	global_load_dwordx4 v[162:165], v182, s[44:45]
	s_waitcnt vmcnt(5)
	v_lshlrev_b32_e32 v184, 16, v166
	v_and_b32_e32 v185, 0xffff0000, v166
	v_lshlrev_b32_e32 v166, 16, v167
	v_and_b32_e32 v167, 0xffff0000, v167
	v_lshlrev_b32_e32 v182, 16, v168
	v_and_b32_e32 v183, 0xffff0000, v168
	v_lshlrev_b32_e32 v168, 16, v169
	v_and_b32_e32 v169, 0xffff0000, v169
	v_pk_mul_f32 v[160:161], v[160:161], v[166:167]
	v_pk_mul_f32 v[158:159], v[158:159], v[184:185]
	s_waitcnt vmcnt(4)
	v_lshlrev_b32_e32 v186, 16, v170
	v_and_b32_e32 v187, 0xffff0000, v170
	v_lshlrev_b32_e32 v170, 16, v171
	v_and_b32_e32 v171, 0xffff0000, v171
	s_waitcnt vmcnt(3)
	v_lshlrev_b32_e32 v188, 16, v174
	v_and_b32_e32 v189, 0xffff0000, v174
	v_lshlrev_b32_e32 v174, 16, v175
	v_and_b32_e32 v175, 0xffff0000, v175
	s_waitcnt vmcnt(2)
	v_lshlrev_b32_e32 v190, 16, v176
	s_waitcnt vmcnt(0)
	v_pk_fma_f32 v[158:159], v[162:163], v[182:183], v[158:159]
	v_pk_fma_f32 v[160:161], v[164:165], v[168:169], v[160:161]
	v_and_b32_e32 v191, 0xffff0000, v176
	v_lshlrev_b32_e32 v176, 16, v177
	v_and_b32_e32 v177, 0xffff0000, v177
	v_lshlrev_b32_e32 v192, 16, v180
	v_and_b32_e32 v193, 0xffff0000, v180
	v_lshlrev_b32_e32 v180, 16, v181
	v_and_b32_e32 v181, 0xffff0000, v181
	v_pk_mul_f32 v[184:185], v[162:163], v[184:185]
	v_pk_mul_f32 v[166:167], v[164:165], v[166:167]
	v_pk_fma_f32 v[160:161], v[160:161], v[170:171], v[174:175]
	v_pk_fma_f32 v[158:159], v[158:159], v[186:187], v[188:189]
	v_pk_fma_f32 v[162:163], v[166:167], v[176:177], v[180:181]
	v_pk_fma_f32 v[164:165], v[184:185], v[190:191], v[192:193]
	v_cvt_pk_bf16_f32 v158, v158, v159
	v_cvt_pk_bf16_f32 v159, v160, v161
	v_cvt_pk_bf16_f32 v164, v164, v165
	v_cvt_pk_bf16_f32 v165, v162, v163
	global_store_dwordx2 v[172:173], v[158:159], off
	global_store_dwordx2 v[178:179], v[164:165], off
	s_branch .LBB0_349
; #define LAS __attribute__((address_space(3)))
; __device__ __forceinline__ float bf_lo(unsigned u) { return __uint_as_float(u << 16); }
; __device__ __forceinline__ float bf_hi(unsigned u) { return __uint_as_float(u & 0xffff0000u); }
; template <int PH> ...
;     ...
;         for (int r = 0; r < 31; ++r) if (r < ntap + 15) {
;             const unsigned v = *(const LAS unsigned*)(lds + ((34 + 16 * PH + kb + r) & 63) * 2048 + tid * 4);
;             const f32x2 x = (f32x2){bf_lo(v), bf_hi(v)};
; __device__ __forceinline__ void conv31_phase(LAS unsigned char* lds, const bf16_t* GLU, bf16_t* SZB, const float* cw, const float* cb, const float* lng, const float* lnb, int G, int c, const int widx) {
;     ...
;             for (int q = 0; q < 6; ++q) { const int i = tf + (h * 6 + q) * 512, r = (i >> 7) < 46 ? (i >> 7) : 45; const int gr = (tpos - 30 + r >= 0) ? (T0 - 30 + r) : T0;
;                 tv[q] = *(const u32x4*)(GLU + (size_t)gr * 1024 + (i & 127) * 8); }
; #pragma unroll
;             for (int q = 0; q < 6; ++q) { const int i = tf + (h * 6 + q) * 512, r = i >> 7;
;                 if (r < 46) *(LAS u32x4*)(lds + ((34 + r) & 63) * 2048 + (i & 127) * 16) = (tpos - 30 + r >= 0) ? tv[q] : (u32x4){0u, 0u, 0u, 0u}; }
.LBB0_352:
	s_or_b64 exec, exec, s[0:1]
	s_mov_b32 s6, s98
	s_waitcnt vmcnt(0)
	v_and_b32_e32 v1, 0xffff0000, v0
	v_lshlrev_b32_e32 v0, 16, v0
	v_and_b32_e32 v3, 0xffff0000, v2
	v_lshlrev_b32_e32 v2, 16, v2
	v_and_b32_e32 v5, 0xffff0000, v4
	v_lshlrev_b32_e32 v4, 16, v4
	v_and_b32_e32 v7, 0xffff0000, v6
	v_lshlrev_b32_e32 v6, 16, v6
	v_and_b32_e32 v9, 0xffff0000, v8
	v_lshlrev_b32_e32 v8, 16, v8
	v_and_b32_e32 v11, 0xffff0000, v10
	v_lshlrev_b32_e32 v10, 16, v10
	v_and_b32_e32 v13, 0xffff0000, v12
	v_lshlrev_b32_e32 v12, 16, v12
	v_and_b32_e32 v15, 0xffff0000, v14
	v_lshlrev_b32_e32 v14, 16, v14
	v_and_b32_e32 v17, 0xffff0000, v16
	v_lshlrev_b32_e32 v16, 16, v16
	v_and_b32_e32 v19, 0xffff0000, v18
	v_lshlrev_b32_e32 v18, 16, v18
	v_and_b32_e32 v21, 0xffff0000, v20
	v_lshlrev_b32_e32 v20, 16, v20
	v_and_b32_e32 v23, 0xffff0000, v22
	v_lshlrev_b32_e32 v22, 16, v22
	v_and_b32_e32 v25, 0xffff0000, v24
	v_lshlrev_b32_e32 v24, 16, v24
	v_and_b32_e32 v27, 0xffff0000, v26
	v_lshlrev_b32_e32 v26, 16, v26
	v_and_b32_e32 v29, 0xffff0000, v28
	v_lshlrev_b32_e32 v28, 16, v28
	v_and_b32_e32 v31, 0xffff0000, v30
	v_lshlrev_b32_e32 v30, 16, v30
	v_and_b32_e32 v33, 0xffff0000, v32
	v_lshlrev_b32_e32 v32, 16, v32
	v_and_b32_e32 v35, 0xffff0000, v34
	v_lshlrev_b32_e32 v34, 16, v34
	v_and_b32_e32 v37, 0xffff0000, v36
	v_lshlrev_b32_e32 v36, 16, v36
	v_and_b32_e32 v39, 0xffff0000, v38
	v_lshlrev_b32_e32 v38, 16, v38
	v_and_b32_e32 v41, 0xffff0000, v40
	v_lshlrev_b32_e32 v40, 16, v40
	v_and_b32_e32 v43, 0xffff0000, v42
	v_lshlrev_b32_e32 v42, 16, v42
	v_and_b32_e32 v45, 0xffff0000, v44
	v_lshlrev_b32_e32 v44, 16, v44
	v_and_b32_e32 v47, 0xffff0000, v46
	v_lshlrev_b32_e32 v46, 16, v46
	v_and_b32_e32 v49, 0xffff0000, v48
	v_lshlrev_b32_e32 v48, 16, v48
	v_and_b32_e32 v51, 0xffff0000, v50
	v_lshlrev_b32_e32 v50, 16, v50
	v_and_b32_e32 v53, 0xffff0000, v52
	v_lshlrev_b32_e32 v52, 16, v52
	v_and_b32_e32 v55, 0xffff0000, v54
	v_lshlrev_b32_e32 v54, 16, v54
	v_and_b32_e32 v57, 0xffff0000, v56
	v_lshlrev_b32_e32 v56, 16, v56
	v_and_b32_e32 v59, 0xffff0000, v58
	v_lshlrev_b32_e32 v58, 16, v58
	v_and_b32_e32 v61, 0xffff0000, v60
	v_lshlrev_b32_e32 v60, 16, v60
	v_and_b32_e32 v63, 0xffff0000, v62
	v_lshlrev_b32_e32 v62, 16, v62
	v_and_b32_e32 v65, 0xffff0000, v64
	v_lshlrev_b32_e32 v64, 16, v64
	v_and_b32_e32 v67, 0xffff0000, v66
	v_lshlrev_b32_e32 v66, 16, v66
	v_and_b32_e32 v69, 0xffff0000, v68
	v_lshlrev_b32_e32 v68, 16, v68
	v_and_b32_e32 v71, 0xffff0000, v70
	v_lshlrev_b32_e32 v70, 16, v70
	v_and_b32_e32 v73, 0xffff0000, v72
	v_lshlrev_b32_e32 v72, 16, v72
	v_and_b32_e32 v75, 0xffff0000, v74
	v_lshlrev_b32_e32 v74, 16, v74
	v_and_b32_e32 v77, 0xffff0000, v76
	v_lshlrev_b32_e32 v76, 16, v76
	v_and_b32_e32 v79, 0xffff0000, v78
	v_lshlrev_b32_e32 v78, 16, v78
	v_and_b32_e32 v81, 0xffff0000, v80
	v_lshlrev_b32_e32 v80, 16, v80
	v_and_b32_e32 v83, 0xffff0000, v82
	v_lshlrev_b32_e32 v82, 16, v82
	v_and_b32_e32 v85, 0xffff0000, v84
	v_lshlrev_b32_e32 v84, 16, v84
	v_and_b32_e32 v87, 0xffff0000, v86
	v_lshlrev_b32_e32 v86, 16, v86
	v_and_b32_e32 v89, 0xffff0000, v88
	v_lshlrev_b32_e32 v88, 16, v88
	v_and_b32_e32 v91, 0xffff0000, v90
	v_lshlrev_b32_e32 v90, 16, v90
	s_mov_b32 s7, 0
	s_mov_b32 s34, s6
